# RWKV prep: g-LoRA output GEMM hoisted out of the row-block loop (16 weight fragments loaded once per tile instead of per 16-row block)
# speedup vs baseline: 1.0111x; 1.0063x over previous
; #define LAS __attribute__((address_space(3)))
; __device__ __forceinline__ void st_bf4(bf16_t* p, f32x4 v) { u32x2 w; w.x = cvt_pk_bf16(v[0], v[1]); w.y = cvt_pk_bf16(v[2], v[3]); *(u32x2*)p = w; }
; __device__ __forceinline__ void rwkv_prep_tile(LAS unsigned char* lds, const PrepArgs& P, int tt, int tid) {
;     ...
;     const int h = wave, cb = 64 * h; const int b_ = t0 >> 12, p = b_ * 8 + h;
; #pragma unroll 1
;     for (int m = 0; m < 4; ++m) {
;         const int i = 16 * m + fr; const bf16_t* Ut = P.U + (size_t)(t0 + i) * 1792; const bool hp = (s0 + i) > 0;
;         int fq4 = 4 * fq; asm volatile("" : "+v"(fq4));
;         u32x2 uk[4], pk[4], ur[4], pr[4], uv[4], pv[4]; f32x4 vf[4];
;         { const bf16_t* Up = hp ? Ut - 1792 : Ut; const unsigned pm = hp ? 0xffffffffu : 0u;
; #pragma unroll
;           for (int n = 0; n < 4; ++n) { const int c = cb + 16 * n + fq4;
;               uk[n] = *(const u32x2*)(Ut + 512 + c); ur[n] = *(const u32x2*)(Ut + c); uv[n] = *(const u32x2*)(Ut + 1024 + c);
;               pk[n] = *(const u32x2*)(Up + 512 + c); pr[n] = *(const u32x2*)(Up + c); pv[n] = *(const u32x2*)(Up + 1024 + c);
;               if (P.layer > 0) vf[n] = *(const f32x4*)(P.vfirst + (size_t)(t0 + i) * 512 + c); }
; #pragma unroll
;           for (int n = 0; n < 4; ++n) { pk[n].x &= pm; pk[n].y &= pm; pr[n].x &= pm; pr[n].y &= pm; pv[n].x &= pm; pv[n].y &= pm; } }
;         f32x4 aa[4], acc[4];
;         row_gemm<64>(aa, LAa + i * SW, P.a2t + (size_t)cb * 64, fr, fq);
;         row_gemm<64>(acc, LAw + i * SW, P.w2t + (size_t)cb * 64, fr, fq);
; #pragma unroll
;         for (int n = 0; n < 4; ++n) { const f32x4 a0v = *(LAS const f32x4*)(PRM + 1536 + cb + 16 * n + fq4), w0v = *(LAS const f32x4*)(PRM + 2048 + cb + 16 * n + fq4); f32x4 d;
; #pragma unroll
;             for (int j = 0; j < 4; ++j) { aa[n][j] = sigmoidf_(aa[n][j] + a0v[j]); d[j] = __expf(-0.6065306597f * sigmoidf_(acc[n][j] + w0v[j])); }
;             *(f32x4*)(P.Wd + ((size_t)p * SEQ + s0 + i) * 64 + 4 * fq4 + 4 * n) = d; }
;         row_gemm<128>(acc, LAg + i * SG, P.g2t + (size_t)cb * 128, fr, fq);
; #pragma unroll
;         for (int n = 0; n < 4; ++n) st_bf4(P.Go + (size_t)(t0 + i) * 512 + cb + 16 * n + fq4, acc[n]);
;         if (P.layer > 0) row_gemm<32>(acc, LAvv + i * SVV, P.v2t + (size_t)cb * 32, fr, fq);
.LBB0_415:
	s_add_u32 s16, s28, 0x5b00000
	s_addc_u32 s17, s29, 0
	s_ashr_i32 s6, s21, 3
	s_ashr_i32 s22, s20, 6
	s_and_b32 s18, s20, 0xffffffc0
	s_and_b32 s6, s6, -8
	s_add_i32 s6, s6, s22
	s_lshl_b32 s7, s18, 2
	s_ashr_i32 s19, s18, 31
	s_add_i32 s34, s7, 0
	s_ashr_i32 s7, s6, 31
	s_lshl_b64 s[24:25], s[18:19], 6
	s_add_i32 s31, s34, 0x1bc00
	s_add_i32 s34, s34, 0x1c400
	s_lshl_b64 s[8:9], s[6:7], 12
	s_lshl_b64 s[52:53], s[18:19], 8
	s_ashr_i32 s23, s22, 31
	s_or_b32 s38, s18, 16
	s_or_b32 s39, s18, 32
	s_or_b32 s44, s18, 48
	s_lshl_b64 s[20:21], s[18:19], 1
	s_add_u32 s20, s28, s20
	s_addc_u32 s21, s29, s21
	s_add_u32 s20, s20, 0x7f00000
	s_addc_u32 s21, s21, 0
	s_lshl_b64 s[22:23], s[22:23], 2
	s_add_u32 s22, s28, s22
	s_addc_u32 s23, s29, s23
	s_add_u32 s22, s22, 0x8f00000
	s_addc_u32 s23, s23, 0
	s_lshl_b64 s[54:55], s[18:19], 7
	s_add_u32 s54, s28, s54
	v_lshlrev_b64 v[2:3], 1, v[2:3]
	s_addc_u32 s55, s29, s55
	v_lshlrev_b32_e32 v209, 2, v8
	v_lshlrev_b32_e32 v4, 7, v106
	v_cmp_eq_u32_e64 s[6:7], 0, v8
	v_lshl_add_u64 v[8:9], s[54:55], 0, v[2:3]
	s_mov_b64 s[54:55], 0x3a10000
	v_lshl_add_u64 v[10:11], v[8:9], 0, s[54:55]
	v_mov_b32_e32 v5, v1
	v_or_b32_e32 v12, 0x1000, v4
	v_mov_b32_e32 v13, v1
	v_or_b32_e32 v14, 0x1800, v4
	v_mov_b32_e32 v15, v1
	s_mov_b64 s[54:55], 0x3a10040
	s_add_u32 s52, s28, s52
	v_lshl_add_u64 v[108:109], v[10:11], 0, v[4:5]
	v_lshl_add_u64 v[110:111], v[10:11], 0, v[12:13]
	v_lshl_add_u64 v[112:113], v[10:11], 0, v[14:15]
	v_lshl_add_u64 v[10:11], v[8:9], 0, s[54:55]
	s_mov_b64 s[54:55], 0x3a00000
	s_addc_u32 s53, s29, s53
	v_lshl_add_u64 v[114:115], v[10:11], 0, v[12:13]
	v_lshl_add_u64 v[116:117], v[10:11], 0, v[14:15]
	v_lshl_add_u64 v[10:11], v[8:9], 0, s[54:55]
	s_mov_b64 s[54:55], 0x3a00040
	s_add_u32 s24, s28, s24
	v_lshl_add_u64 v[118:119], v[10:11], 0, v[4:5]
	v_lshl_add_u64 v[4:5], v[8:9], 0, s[54:55]
	s_addc_u32 s25, s29, s25
	v_lshlrev_b32_e32 v0, 6, v106
	v_lshl_add_u64 v[124:125], v[4:5], 0, v[12:13]
	v_lshl_add_u64 v[126:127], v[4:5], 0, v[14:15]
	v_lshl_add_u64 v[4:5], s[52:53], 0, v[2:3]
	v_lshl_add_u64 v[2:3], s[24:25], 0, v[2:3]
	v_lshl_add_u64 v[2:3], v[2:3], 0, v[0:1]
	s_mov_b64 s[24:25], 0x3a48000
	v_lshl_add_u64 v[154:155], v[2:3], 0, s[24:25]
	s_add_i32 s24, 0, 0x19000
	s_mov_b64 s[52:53], 0x3a20000
	v_mov_b32_e32 v0, s24
	s_movk_i32 s24, 0x50
	v_lshlrev_b32_e32 v6, 8, v106
	v_lshl_add_u64 v[8:9], v[4:5], 0, s[52:53]
	v_mov_b32_e32 v7, v1
	v_mad_u32_u24 v0, v106, s24, v0
	v_readlane_b32 s24, v255, 11
	v_lshl_add_u64 v[120:121], v[10:11], 0, v[12:13]
	v_lshl_add_u64 v[122:123], v[10:11], 0, v[14:15]
	v_lshl_add_u64 v[128:129], v[8:9], 0, v[6:7]
	v_or_b32_e32 v10, 0x1000, v6
	v_mov_b32_e32 v11, v1
	v_or_b32_e32 v12, 0x2000, v6
	v_or_b32_e32 v6, 0x3000, v6
	s_mov_b64 s[52:53], 0x3a20040
	v_mov_b32_e32 v2, s24
	s_movk_i32 s24, 0x110
	v_lshl_add_u64 v[130:131], v[8:9], 0, v[10:11]
	v_lshl_add_u64 v[132:133], v[8:9], 0, v[12:13]
	v_lshl_add_u64 v[134:135], v[8:9], 0, v[6:7]
	v_lshl_add_u64 v[8:9], v[4:5], 0, s[52:53]
	s_mov_b64 s[52:53], 0x3a20080
	v_mad_u32_u24 v210, v106, s24, v2
	s_and_b32 s24, s27, 7
	v_lshl_add_u64 v[136:137], v[8:9], 0, v[10:11]
	v_lshl_add_u64 v[138:139], v[8:9], 0, v[12:13]
	v_lshl_add_u64 v[140:141], v[8:9], 0, v[6:7]
	v_lshl_add_u64 v[8:9], v[4:5], 0, s[52:53]
	s_mov_b64 s[52:53], 0x3a200c0
	s_lshl_b32 s24, s24, 11
	s_lshl_b32 s25, s30, 6
	s_or_b32 s8, s8, s26
	v_mov_b32_e32 v107, v1
	v_lshl_add_u64 v[4:5], v[4:5], 0, s[52:53]
	s_add_i32 s24, s24, s25
	v_lshl_add_u64 v[2:3], s[8:9], 0, v[106:107]
	v_readlane_b32 s8, v254, 55
	v_lshl_add_u64 v[148:149], v[4:5], 0, v[10:11]
	v_lshl_add_u64 v[150:151], v[4:5], 0, v[12:13]
	v_lshl_add_u64 v[152:153], v[4:5], 0, v[6:7]
	v_or_b32_e32 v211, s24, v106
	s_movk_i32 s24, 0x90
	v_lshlrev_b64 v[4:5], 8, v[2:3]
	v_lshlrev_b64 v[2:3], 9, v[2:3]
	v_readlane_b32 s9, v254, 56
	s_mov_b32 s35, 0
	v_lshl_add_u64 v[142:143], v[8:9], 0, v[10:11]
	v_lshl_add_u64 v[144:145], v[8:9], 0, v[12:13]
	v_lshl_add_u64 v[146:147], v[8:9], 0, v[6:7]
	v_mad_u32_u24 v212, v106, s24, 0
	v_lshl_add_u64 v[156:157], s[92:93], 0, v[4:5]
	v_lshl_add_u64 v[158:159], s[8:9], 0, v[2:3]
	s_waitcnt lgkmcnt(0)
	s_barrier
	global_load_dwordx4 v[18:21], v[128:129], off
	global_load_dwordx4 v[22:25], v[128:129], off offset:64
	global_load_dwordx4 v[26:29], v[128:129], off offset:128
	global_load_dwordx4 v[30:33], v[128:129], off offset:192
	global_load_dwordx4 v[34:37], v[130:131], off
	global_load_dwordx4 v[38:41], v[136:137], off
	global_load_dwordx4 v[42:45], v[142:143], off
	global_load_dwordx4 v[46:49], v[148:149], off
	global_load_dwordx4 v[50:53], v[132:133], off
	global_load_dwordx4 v[54:57], v[138:139], off
	global_load_dwordx4 v[58:61], v[144:145], off
	global_load_dwordx4 v[62:65], v[150:151], off
	global_load_dwordx4 v[66:69], v[134:135], off
	global_load_dwordx4 v[70:73], v[140:141], off
	global_load_dwordx4 v[74:77], v[146:147], off
	global_load_dwordx4 v[78:81], v[152:153], off
	s_mov_b32 s46, 0
	v_mov_b32_e32 v176, v210
	s_waitcnt vmcnt(0)
; #define LAS __attribute__((address_space(3)))
; __device__ __forceinline__ void st_bf4(bf16_t* p, f32x4 v) { u32x2 w; w.x = cvt_pk_bf16(v[0], v[1]); w.y = cvt_pk_bf16(v[2], v[3]); *(u32x2*)p = w; }
; __device__ __forceinline__ f32x4 mfma16(bf16x8 a, bf16x8 b, f32x4 c) { return __builtin_amdgcn_mfma_f32_16x16x32_bf16(a, b, c, 0, 0, 0); }
; template <int K>
; __device__ __forceinline__ void row_gemm(f32x4 (&acc)[4], LAS const unsigned char* Arow, const bf16_t* Bt, int fr, int fq) {
;     bf16x8 bw[K / 32][4];
; #pragma unroll
;     for (int ks = 0; ks < K / 32; ++ks)
; #pragma unroll
;         for (int n = 0; n < 4; ++n) bw[ks][n] = *(const bf16x8*)(Bt + (size_t)(16 * n + fr) * K + ks * 32 + fq * 8);
; #pragma unroll
;     for (int n = 0; n < 4; ++n) acc[n] = (f32x4){0.f, 0.f, 0.f, 0.f};
; #pragma unroll
;     for (int ks = 0; ks < K / 32; ++ks) { const bf16x8 a = *(LAS const bf16x8*)(Arow + (ks * 32 + fq * 8) * 2);
; #pragma unroll
;         for (int n = 0; n < 4; ++n) acc[n] = mfma16(bw[ks][n], a, acc[n]); }
; }
; __device__ __forceinline__ void rwkv_prep_tile(LAS unsigned char* lds, const PrepArgs& P, int tt, int tid) {
;     ...
;         row_gemm<128>(acc, LAg + i * SG, P.g2t + (size_t)cb * 128, fr, fq);
; #pragma unroll
;         for (int n = 0; n < 4; ++n) st_bf4(P.Go + (size_t)(t0 + i) * 512 + cb + 16 * n + fq4, acc[n]);
.Lp4g_loop:
	v_add_u32_e32 v177, v176, v208
	ds_read_b128 v[82:85], v177
	ds_read_b128 v[86:89], v177 offset:64
	ds_read_b128 v[90:93], v177 offset:128
	ds_read_b128 v[94:97], v177 offset:192
	v_add_u32_e32 v178, s46, v211
	v_lshlrev_b32_e32 v178, 10, v178
	v_lshl_add_u32 v179, v209, 1, v178
	s_waitcnt lgkmcnt(0)
	v_mfma_f32_16x16x32_bf16 v[160:163], v[18:21], v[82:85], 0
	v_mfma_f32_16x16x32_bf16 v[164:167], v[34:37], v[82:85], 0
	v_mfma_f32_16x16x32_bf16 v[168:171], v[50:53], v[82:85], 0
	v_mfma_f32_16x16x32_bf16 v[172:175], v[66:69], v[82:85], 0
	v_mfma_f32_16x16x32_bf16 v[160:163], v[22:25], v[86:89], v[160:163]
	v_mfma_f32_16x16x32_bf16 v[164:167], v[38:41], v[86:89], v[164:167]
	v_mfma_f32_16x16x32_bf16 v[168:171], v[54:57], v[86:89], v[168:171]
	v_mfma_f32_16x16x32_bf16 v[172:175], v[70:73], v[86:89], v[172:175]
	v_mfma_f32_16x16x32_bf16 v[160:163], v[26:29], v[90:93], v[160:163]
	v_mfma_f32_16x16x32_bf16 v[164:167], v[42:45], v[90:93], v[164:167]
	v_mfma_f32_16x16x32_bf16 v[168:171], v[58:61], v[90:93], v[168:171]
	v_mfma_f32_16x16x32_bf16 v[172:175], v[74:77], v[90:93], v[172:175]
	v_mfma_f32_16x16x32_bf16 v[160:163], v[30:33], v[94:97], v[160:163]
	v_mfma_f32_16x16x32_bf16 v[164:167], v[46:49], v[94:97], v[164:167]
	v_mfma_f32_16x16x32_bf16 v[168:171], v[62:65], v[94:97], v[168:171]
	v_mfma_f32_16x16x32_bf16 v[172:175], v[78:81], v[94:97], v[172:175]
	s_nop 7
	s_nop 7
	v_cvt_pk_bf16_f32 v180, v160, v161
	v_cvt_pk_bf16_f32 v181, v162, v163
	global_store_dwordx2 v179, v[180:181], s[20:21]
	v_cvt_pk_bf16_f32 v182, v164, v165
	v_cvt_pk_bf16_f32 v183, v166, v167
	global_store_dwordx2 v179, v[182:183], s[20:21] offset:32
	v_cvt_pk_bf16_f32 v184, v168, v169
	v_cvt_pk_bf16_f32 v185, v170, v171
	global_store_dwordx2 v179, v[184:185], s[20:21] offset:64
	v_cvt_pk_bf16_f32 v186, v172, v173
	v_cvt_pk_bf16_f32 v187, v174, v175
	global_store_dwordx2 v179, v[186:187], s[20:21] offset:96
	v_add_u32_e32 v176, 0x1100, v176
	s_add_i32 s46, s46, 16
	s_cmp_lg_u32 s46, 64
	s_cbranch_scc1 .Lp4g_loop
	s_branch .LBB0_417

; #define LAS __attribute__((address_space(3)))
; __device__ __forceinline__ float sigmoidf_(float x) { return __builtin_amdgcn_rcpf(1.0f + __expf(-x)); }
; __device__ __forceinline__ void rwkv_prep_tile(LAS unsigned char* lds, const PrepArgs& P, int tt, int tid) {
;     ...
;         row_gemm<64>(aa, LAa + i * SW, P.a2t + (size_t)cb * 64, fr, fq);
;         row_gemm<64>(acc, LAw + i * SW, P.w2t + (size_t)cb * 64, fr, fq);
; #pragma unroll
;         for (int n = 0; n < 4; ++n) { const f32x4 a0v = *(LAS const f32x4*)(PRM + 1536 + cb + 16 * n + fq4), w0v = *(LAS const f32x4*)(PRM + 2048 + cb + 16 * n + fq4); f32x4 d;
; #pragma unroll
;             for (int j = 0; j < 4; ++j) { aa[n][j] = sigmoidf_(aa[n][j] + a0v[j]); d[j] = __expf(-0.6065306597f * sigmoidf_(acc[n][j] + w0v[j])); }
;             *(f32x4*)(P.Wd + ((size_t)p * SEQ + s0 + i) * 64 + 4 * fq4 + 4 * n) = d; }
.LBB0_425:
	global_load_dwordx4 v[18:21], v[108:109], off
	global_load_dwordx4 v[22:25], v[108:109], off offset:2048
	global_load_dwordx4 v[26:29], v[110:111], off
	v_add_u32_e32 v62, v212, v208
	ds_read_b128 v[34:37], v62 offset:9216
	ds_read_b128 v[30:33], v62 offset:9280
	global_load_dwordx4 v[38:41], v[108:109], off offset:64
	global_load_dwordx4 v[42:45], v[112:113], off
	global_load_dwordx4 v[46:49], v[108:109], off offset:2112
	global_load_dwordx4 v[50:53], v[118:119], off
	global_load_dwordx4 v[58:61], v[118:119], off offset:64
	v_lshlrev_b32_e32 v162, 2, v98
	v_add_u32_e32 v71, s34, v162
	v_lshl_add_u64 v[88:89], v[156:157], 0, s[10:11]
	v_ashrrev_i32_e32 v163, 31, v162
	s_mov_b32 s24, 0xe100000
	v_ashrrev_i32_e32 v99, 31, v98
	s_waitcnt vmcnt(7) lgkmcnt(1)
	v_mfma_f32_16x16x32_bf16 v[18:21], v[18:21], v[34:37], 0
	s_waitcnt vmcnt(5)
	v_mfma_f32_16x16x32_bf16 v[54:57], v[26:29], v[34:37], 0
	global_load_dwordx4 v[26:29], v[118:119], off offset:2048
	v_mfma_f32_16x16x32_bf16 v[22:25], v[22:25], v[34:37], 0
	s_waitcnt vmcnt(4)
	v_mfma_f32_16x16x32_bf16 v[34:37], v[42:45], v[34:37], 0
	ds_read_b128 v[42:45], v62
	ds_read_b128 v[62:65], v62 offset:64
	global_load_dwordx4 v[66:69], v[120:121], off
	global_load_dwordx4 v[76:79], v[118:119], off offset:2112
	s_waitcnt vmcnt(4) lgkmcnt(1)
	v_mfma_f32_16x16x32_bf16 v[50:53], v[50:53], v[42:45], 0
	v_mfma_f32_16x16x32_bf16 v[22:25], v[46:49], v[30:33], v[22:25]
	s_waitcnt vmcnt(3) lgkmcnt(0)
	v_mfma_f32_16x16x32_bf16 v[50:53], v[58:61], v[62:65], v[50:53]
	v_lshl_add_u64 v[58:59], v[162:163], 2, v[88:89]
	v_add_co_u32_e32 v58, vcc, s24, v58
	s_waitcnt vmcnt(1)
	v_mfma_f32_16x16x32_bf16 v[66:69], v[66:69], v[42:45], 0
	v_addc_co_u32_e32 v59, vcc, 0, v59, vcc
	s_and_b64 vcc, exec, s[4:5]
	v_mfma_f32_16x16x32_bf16 v[94:97], v[26:29], v[42:45], 0
	global_load_dwordx4 v[26:29], v[122:123], off
	s_waitcnt vmcnt(1)
	v_mfma_f32_16x16x32_bf16 v[76:79], v[76:79], v[62:65], v[94:97]
	s_waitcnt vmcnt(0)
	v_mfma_f32_16x16x32_bf16 v[42:45], v[26:29], v[42:45], 0
	v_mfma_f32_16x16x32_bf16 v[26:29], v[38:41], v[30:33], v[18:21]
	s_nop 2
	global_load_dwordx4 v[18:21], v[114:115], off
	global_load_dwordx4 v[46:49], v[124:125], off
	global_load_dwordx4 v[38:41], v[116:117], off
	s_waitcnt vmcnt(1)
	v_mfma_f32_16x16x32_bf16 v[46:49], v[46:49], v[62:65], v[66:69]
	v_mfma_f32_16x16x32_bf16 v[18:21], v[18:21], v[30:33], v[54:57]
	s_nop 2
	global_load_dwordx4 v[54:57], v[126:127], off
	ds_read_b128 v[94:97], v71
	ds_read_b128 v[204:207], v71 offset:64
	s_waitcnt vmcnt(1)
	v_mfma_f32_16x16x32_bf16 v[30:33], v[38:41], v[30:33], v[34:37]
	s_waitcnt lgkmcnt(1)
	v_add_f32_e32 v50, v50, v94
	v_add_f32_e32 v51, v51, v95
	v_add_f32_e32 v52, v52, v96
	v_add_f32_e32 v53, v53, v97
	v_mul_f32_e32 v50, 0xbfb8aa3b, v50
	v_mul_f32_e32 v51, 0xbfb8aa3b, v51
	v_mul_f32_e32 v52, 0xbfb8aa3b, v52
	v_mul_f32_e32 v53, 0xbfb8aa3b, v53
	v_exp_f32_e32 v50, v50
	v_exp_f32_e32 v51, v51
	v_exp_f32_e32 v52, v52
	v_exp_f32_e32 v53, v53
	v_add_f32_e32 v50, 1.0, v50
	v_add_f32_e32 v51, 1.0, v51
	v_add_f32_e32 v52, 1.0, v52
	v_add_f32_e32 v53, 1.0, v53
	v_rcp_f32_e32 v50, v50
	v_rcp_f32_e32 v51, v51
	v_rcp_f32_e32 v52, v52
	v_rcp_f32_e32 v53, v53
	v_mul_f32_e32 v50, 0xbf1b4598, v50
	v_mul_f32_e32 v51, 0xbf1b4598, v51
	v_mul_f32_e32 v52, 0xbf1b4598, v52
	v_mul_f32_e32 v53, 0xbf1b4598, v53
	v_mul_f32_e32 v50, 0x3fb8aa3b, v50
	v_mul_f32_e32 v51, 0x3fb8aa3b, v51
	v_mul_f32_e32 v52, 0x3fb8aa3b, v52
	v_mul_f32_e32 v53, 0x3fb8aa3b, v53
	v_exp_f32_e32 v50, v50
	v_exp_f32_e32 v51, v51
	v_exp_f32_e32 v52, v52
	v_exp_f32_e32 v53, v53
	s_waitcnt vmcnt(0)
	v_mfma_f32_16x16x32_bf16 v[42:45], v[54:57], v[62:65], v[42:45]
	ds_read_b128 v[60:63], v71 offset:128
	ds_read_b128 v[64:67], v71 offset:192
	s_waitcnt lgkmcnt(2)
; #define LAS __attribute__((address_space(3)))
; __device__ __forceinline__ void st_bf4(bf16_t* p, f32x4 v) { u32x2 w; w.x = cvt_pk_bf16(v[0], v[1]); w.y = cvt_pk_bf16(v[2], v[3]); *(u32x2*)p = w; }
; __device__ __forceinline__ float sigmoidf_(float x) { return __builtin_amdgcn_rcpf(1.0f + __expf(-x)); }
; __device__ __forceinline__ void rwkv_prep_tile(LAS unsigned char* lds, const PrepArgs& P, int tt, int tid) {
;     ...
;         for (int n = 0; n < 4; ++n) { const f32x4 a0v = *(LAS const f32x4*)(PRM + 1536 + cb + 16 * n + fq4), w0v = *(LAS const f32x4*)(PRM + 2048 + cb + 16 * n + fq4); f32x4 d;
; #pragma unroll
;             for (int j = 0; j < 4; ++j) { aa[n][j] = sigmoidf_(aa[n][j] + a0v[j]); d[j] = __expf(-0.6065306597f * sigmoidf_(acc[n][j] + w0v[j])); }
;             *(f32x4*)(P.Wd + ((size_t)p * SEQ + s0 + i) * 64 + 4 * fq4 + 4 * n) = d; }
;         row_gemm<128>(acc, LAg + i * SG, P.g2t + (size_t)cb * 128, fr, fq);
; #pragma unroll
;         for (int n = 0; n < 4; ++n) st_bf4(P.Go + (size_t)(t0 + i) * 512 + cb + 16 * n + fq4, acc[n]);
;         if (P.layer > 0) row_gemm<32>(acc, LAvv + i * SVV, P.v2t + (size_t)cb * 32, fr, fq);
	v_add_f32_e32 v54, v76, v204
	v_add_f32_e32 v55, v77, v205
	v_add_f32_e32 v56, v78, v206
	v_add_f32_e32 v57, v79, v207
	v_mul_f32_e32 v54, 0xbfb8aa3b, v54
	v_mul_f32_e32 v55, 0xbfb8aa3b, v55
	v_mul_f32_e32 v56, 0xbfb8aa3b, v56
	v_mul_f32_e32 v57, 0xbfb8aa3b, v57
	s_waitcnt lgkmcnt(1)
	v_add_f32_e32 v46, v46, v60
	v_add_f32_e32 v47, v47, v61
	v_add_f32_e32 v48, v48, v62
	v_add_f32_e32 v49, v49, v63
	v_exp_f32_e32 v54, v54
	v_exp_f32_e32 v55, v55
	v_exp_f32_e32 v56, v56
	v_exp_f32_e32 v57, v57
	v_mul_f32_e32 v46, 0xbfb8aa3b, v46
	v_mul_f32_e32 v47, 0xbfb8aa3b, v47
	v_mul_f32_e32 v48, 0xbfb8aa3b, v48
	v_mul_f32_e32 v49, 0xbfb8aa3b, v49
	s_waitcnt lgkmcnt(0)
	v_add_f32_e32 v42, v42, v64
	v_add_f32_e32 v43, v43, v65
	v_add_f32_e32 v44, v44, v66
	v_add_f32_e32 v45, v45, v67
	v_exp_f32_e32 v46, v46
	v_exp_f32_e32 v47, v47
	v_exp_f32_e32 v48, v48
	v_exp_f32_e32 v49, v49
	v_mul_f32_e32 v42, 0xbfb8aa3b, v42
	v_mul_f32_e32 v43, 0xbfb8aa3b, v43
	v_mul_f32_e32 v44, 0xbfb8aa3b, v44
	v_mul_f32_e32 v45, 0xbfb8aa3b, v45
	v_exp_f32_e32 v42, v42
	v_exp_f32_e32 v43, v43
	v_exp_f32_e32 v44, v44
	v_exp_f32_e32 v45, v45
	v_add_f32_e32 v54, 1.0, v54
	v_add_f32_e32 v55, 1.0, v55
	v_add_f32_e32 v56, 1.0, v56
	v_add_f32_e32 v57, 1.0, v57
	v_rcp_f32_e32 v54, v54
	v_rcp_f32_e32 v55, v55
	v_rcp_f32_e32 v56, v56
	v_rcp_f32_e32 v57, v57
	v_add_f32_e32 v46, 1.0, v46
	v_add_f32_e32 v47, 1.0, v47
	v_add_f32_e32 v48, 1.0, v48
	v_add_f32_e32 v49, 1.0, v49
	v_rcp_f32_e32 v46, v46
	v_rcp_f32_e32 v47, v47
	v_rcp_f32_e32 v48, v48
	v_rcp_f32_e32 v49, v49
	v_add_f32_e32 v42, 1.0, v42
	v_add_f32_e32 v43, 1.0, v43
	v_add_f32_e32 v44, 1.0, v44
	v_add_f32_e32 v45, 1.0, v45
	v_rcp_f32_e32 v42, v42
	v_rcp_f32_e32 v43, v43
	v_rcp_f32_e32 v44, v44
	v_rcp_f32_e32 v45, v45
	v_mul_f32_e32 v54, 0xbf1b4598, v54
	v_mul_f32_e32 v55, 0xbf1b4598, v55
	v_mul_f32_e32 v56, 0xbf1b4598, v56
	v_mul_f32_e32 v57, 0xbf1b4598, v57
	v_mul_f32_e32 v54, 0x3fb8aa3b, v54
	v_mul_f32_e32 v55, 0x3fb8aa3b, v55
	v_mul_f32_e32 v56, 0x3fb8aa3b, v56
	v_mul_f32_e32 v57, 0x3fb8aa3b, v57
	v_mul_f32_e32 v46, 0xbf1b4598, v46
	v_mul_f32_e32 v47, 0xbf1b4598, v47
	v_mul_f32_e32 v48, 0xbf1b4598, v48
	v_mul_f32_e32 v49, 0xbf1b4598, v49
	v_exp_f32_e32 v54, v54
	v_exp_f32_e32 v55, v55
	v_exp_f32_e32 v56, v56
	v_exp_f32_e32 v57, v57
	v_mul_f32_e32 v46, 0x3fb8aa3b, v46
	v_mul_f32_e32 v47, 0x3fb8aa3b, v47
	v_mul_f32_e32 v48, 0x3fb8aa3b, v48
	v_mul_f32_e32 v49, 0x3fb8aa3b, v49
	v_mul_f32_e32 v42, 0xbf1b4598, v42
	v_mul_f32_e32 v43, 0xbf1b4598, v43
	v_mul_f32_e32 v44, 0xbf1b4598, v44
	v_mul_f32_e32 v45, 0xbf1b4598, v45
	v_exp_f32_e32 v46, v46
	v_exp_f32_e32 v47, v47
	v_exp_f32_e32 v48, v48
	v_exp_f32_e32 v49, v49
	v_mul_f32_e32 v42, 0x3fb8aa3b, v42
	v_mul_f32_e32 v43, 0x3fb8aa3b, v43
	v_mul_f32_e32 v44, 0x3fb8aa3b, v44
	v_mul_f32_e32 v45, 0x3fb8aa3b, v45
	v_exp_f32_e32 v42, v42
	v_exp_f32_e32 v43, v43
	v_exp_f32_e32 v44, v44
	v_exp_f32_e32 v45, v45
	global_store_dwordx4 v[58:59], v[50:53], off
	global_store_dwordx4 v[58:59], v[54:57], off offset:16
	global_store_dwordx4 v[58:59], v[46:49], off offset:32
	global_store_dwordx4 v[58:59], v[42:45], off offset:48
	s_nop 1
	v_add_u32_e32 v34, s31, v162
	ds_read_b128 v[46:49], v34
	ds_read_b128 v[42:45], v34 offset:64
	ds_read_b128 v[38:41], v34 offset:128
	ds_read_b128 v[34:37], v34 offset:192
	s_cbranch_vccnz .LBB0_427
	global_load_dwordx4 v[50:53], v[154:155], off
	global_load_dwordx4 v[54:57], v[154:155], off offset:1024
	v_add_u32_e32 v58, v0, v208
	ds_read_b128 v[62:65], v58
	s_waitcnt vmcnt(1) lgkmcnt(0)
	v_mfma_f32_16x16x32_bf16 v[66:69], v[50:53], v[62:65], 0
	global_load_dwordx4 v[50:53], v[154:155], off offset:2048
	global_load_dwordx4 v[76:79], v[154:155], off offset:3072
	s_waitcnt vmcnt(2)
	v_mfma_f32_16x16x32_bf16 v[58:61], v[54:57], v[62:65], 0
	s_waitcnt vmcnt(1)
	v_mfma_f32_16x16x32_bf16 v[54:57], v[50:53], v[62:65], 0
	s_waitcnt vmcnt(0)
	v_mfma_f32_16x16x32_bf16 v[62:65], v[76:79], v[62:65], 0
